# P1 h stores sc0 sc1 nt
# speedup vs baseline: 1.0021x; 1.0021x over previous
; #define GAS __attribute__((address_space(1)))
; __global__ void __launch_bounds__(NWAVES * 64) mega_fwd(Args args) {
;     ...
;             for (int rr = wave; rr < 256; rr += NWAVES) {
;                 const size_t row = (size_t)p * 256 + rr;
;                 const GAS f32x4* xr = (const GAS f32x4*)(x + row * D) + lane;
;                 f32x4 v[4]; float s = 0.f;
; #pragma unroll
;                 for (int j = 0; j < 4; ++j) { v[j] = __builtin_nontemporal_load(&xr[64 * j]); s += (v[j].x + v[j].y) + (v[j].z + v[j].w); }
;                 const float mean = wave_sum(s, lane) * (1.f / D); float s2 = 0.f;
; #pragma unroll
;                 for (int j = 0; j < 4; ++j) { v[j] = v[j] - mean; s2 += (v[j].x * v[j].x + v[j].y * v[j].y) + (v[j].z * v[j].z + v[j].w * v[j].w); }
;                 const float rstd = 1.f / sqrtf(wave_sum(s2, lane) * (1.f / D) + LN_EPS);
.LBB0_135:
	global_load_dwordx4 v[16:19], v[54:55], off offset:-3072 nt
	global_load_dwordx4 v[20:23], v[54:55], off offset:-2048 nt
	global_load_dwordx4 v[24:27], v[54:55], off offset:-1024 nt
	global_load_dwordx4 v[28:31], v[54:55], off nt
	s_mov_b64 s[0:1], 0x8000
	v_lshl_add_u64 v[54:55], v[54:55], 0, s[0:1]
	s_add_i32 s31, s31, 8
	s_cmpk_gt_i32 s31, 0xf7
	s_waitcnt vmcnt(3)
	v_mov_b32_e32 v72, v17
	v_mov_b32_e32 v73, v18
	v_mov_b32_e32 v74, v16
	v_mov_b32_e32 v75, v19
	s_waitcnt vmcnt(2)
	v_mov_b32_e32 v76, v21
	v_mov_b32_e32 v77, v22
	v_mov_b32_e32 v78, v20
	v_mov_b32_e32 v79, v23
	v_pk_add_f32 v[72:73], v[72:73], v[74:75]
	v_pk_add_f32 v[74:75], v[76:77], v[78:79]
	v_add_f32_e32 v78, v72, v73
	v_pk_add_f32 v[72:73], v[74:75], v[74:75] op_sel:[0,1] op_sel_hi:[1,0]
	s_waitcnt vmcnt(1)
	v_add_f32_e32 v80, v24, v25
	v_add_f32_e32 v82, v26, v27
	s_waitcnt vmcnt(0)
	v_mov_b32_e32 v85, v28
	v_mov_b32_e32 v81, v30
	v_mov_b32_e32 v83, v31
	v_add_f32_e32 v84, 0, v78
	v_mov_b32_e32 v73, v29
	v_pk_add_f32 v[76:77], v[80:81], v[82:83]
	v_pk_add_f32 v[72:73], v[84:85], v[72:73]
	s_nop 0
	v_pk_add_f32 v[72:73], v[72:73], v[76:77]
	s_nop 0
	v_add_f32_e32 v72, v72, v73
	s_waitcnt lgkmcnt(0)
	s_nop 1
	v_add_f32_dpp v72, v72, v72 quad_perm:[1,0,3,2] row_mask:0xf bank_mask:0xf
	s_waitcnt lgkmcnt(0)
	s_nop 1
	v_add_f32_dpp v72, v72, v72 quad_perm:[2,3,0,1] row_mask:0xf bank_mask:0xf
	s_waitcnt lgkmcnt(0)
	s_nop 1
	v_add_f32_dpp v72, v72, v72 row_half_mirror row_mask:0xf bank_mask:0xf
	s_waitcnt lgkmcnt(0)
	s_nop 1
	v_add_f32_dpp v72, v72, v72 row_mirror row_mask:0xf bank_mask:0xf
	s_waitcnt lgkmcnt(0)
	v_mov_b32_e32 v73, v72
	s_nop 1
	v_permlane16_swap_b32_e32 v72, v73
	v_add_f32_e32 v72, v72, v73
	s_waitcnt lgkmcnt(0)
	v_mov_b32_e32 v73, v72
	s_nop 1
	v_permlane32_swap_b32_e32 v72, v73
	v_add_f32_e32 v72, v72, v73
	v_fmamk_f32 v17, v72, 0xba800000, v17
	v_fmamk_f32 v16, v72, 0xba800000, v16
	v_fmamk_f32 v19, v72, 0xba800000, v19
	v_fmac_f32_e32 v18, 0xba800000, v72
	v_fmamk_f32 v21, v72, 0xba800000, v21
	v_fmamk_f32 v20, v72, 0xba800000, v20
	v_fmamk_f32 v23, v72, 0xba800000, v23
	v_fmac_f32_e32 v22, 0xba800000, v72
	v_fmamk_f32 v25, v72, 0xba800000, v25
	v_fmamk_f32 v24, v72, 0xba800000, v24
	v_fmamk_f32 v27, v72, 0xba800000, v27
	v_fmac_f32_e32 v26, 0xba800000, v72
	v_fmamk_f32 v31, v72, 0xba800000, v31
	v_fmamk_f32 v30, v72, 0xba800000, v30
	v_fmamk_f32 v29, v72, 0xba800000, v29
	v_fmac_f32_e32 v28, 0xba800000, v72
	v_pk_mul_f32 v[72:73], v[18:19], v[18:19]
	v_pk_mul_f32 v[74:75], v[16:17], v[16:17]
	v_pk_mul_f32 v[76:77], v[22:23], v[22:23]
	v_pk_mul_f32 v[78:79], v[20:21], v[20:21]
	v_pk_mov_b32 v[84:85], v[74:75], v[72:73] op_sel:[1,0]
	v_mov_b32_e32 v75, v73
	v_pk_mov_b32 v[72:73], v[78:79], v[76:77] op_sel:[1,0]
	v_mov_b32_e32 v79, v77
	v_mul_f32_e32 v83, v28, v28
	v_mul_f32_e32 v80, v25, v25
	v_mul_f32_e32 v82, v27, v27
	v_pk_add_f32 v[74:75], v[84:85], v[74:75]
	v_pk_add_f32 v[72:73], v[72:73], v[78:79]
	v_mul_f32_e32 v86, v29, v29
	v_mul_f32_e32 v87, v30, v30
	v_mul_f32_e32 v88, v31, v31
	v_pk_fma_f32 v[76:77], v[24:25], v[24:25], v[80:81] op_sel_hi:[1,1,0]
	v_pk_fma_f32 v[80:81], v[26:27], v[26:27], v[82:83] op_sel_hi:[1,1,0]
	v_pk_add_f32 v[74:75], v[74:75], v[74:75] op_sel:[0,1] op_sel_hi:[1,0]
	v_pk_add_f32 v[72:73], v[72:73], v[72:73] op_sel:[0,1] op_sel_hi:[1,0]
	v_mov_b32_e32 v77, v87
	v_mov_b32_e32 v81, v88
	v_mov_b32_e32 v75, v83
	v_mov_b32_e32 v73, v86
	v_pk_add_f32 v[76:77], v[76:77], v[80:81]
	v_pk_add_f32 v[72:73], v[74:75], v[72:73]
	s_nop 0
	v_pk_add_f32 v[72:73], v[72:73], v[76:77]
	s_nop 0
	v_add_f32_e32 v72, v72, v73
	s_waitcnt lgkmcnt(0)
	s_nop 1
	v_add_f32_dpp v72, v72, v72 quad_perm:[1,0,3,2] row_mask:0xf bank_mask:0xf
	s_waitcnt lgkmcnt(0)
	s_nop 1
	v_add_f32_dpp v72, v72, v72 quad_perm:[2,3,0,1] row_mask:0xf bank_mask:0xf
	s_waitcnt lgkmcnt(0)
	s_nop 1
	v_add_f32_dpp v72, v72, v72 row_half_mirror row_mask:0xf bank_mask:0xf
	s_waitcnt lgkmcnt(0)
; #define GAS __attribute__((address_space(1)))
; #define LAS __attribute__((address_space(3)))
; __device__ __forceinline__ unsigned pk2(float lo, float hi) { return f2bf(lo) | (f2bf(hi) << 16); }
; __global__ void __launch_bounds__(NWAVES * 64) mega_fwd(Args args) {
;     ...
;                 const float rstd = 1.f / sqrtf(wave_sum(s2, lane) * (1.f / D) + LN_EPS);
;                 GAS unsigned long long* o8 = (GAS unsigned long long*)(HB + row * D) + lane;
; #pragma unroll
;                 for (int j = 0; j < 4; ++j) { const f32x4 sh = *(const LAS f32x4*)(shsc + 256 * j + 4 * lane), sc = *(const LAS f32x4*)(shsc + 1024 + 256 * j + 4 * lane);
;                     const f32x4 y = v[j] * rstd * (sc + 1.0f) + sh;
;                     o8[64 * j] = (unsigned long long)pk2(y.x, y.y) | ((unsigned long long)pk2(y.z, y.w) << 32); }
	s_nop 1
	v_add_f32_dpp v72, v72, v72 row_mirror row_mask:0xf bank_mask:0xf
	s_waitcnt lgkmcnt(0)
	v_mov_b32_e32 v73, v72
	s_nop 1
	v_permlane16_swap_b32_e32 v72, v73
	v_add_f32_e32 v72, v72, v73
	s_waitcnt lgkmcnt(0)
	v_mov_b32_e32 v73, v72
	s_nop 1
	v_permlane32_swap_b32_e32 v72, v73
	v_add_f32_e32 v72, v72, v73
	v_fmamk_f32 v72, v72, 0x3a800000, v70
	v_mul_f32_e32 v73, 0x4f800000, v72
	v_cmp_gt_f32_e32 vcc, s33, v72
	s_nop 1
	v_cndmask_b32_e32 v72, v72, v73, vcc
	v_sqrt_f32_e32 v73, v72
	s_nop 0
	v_add_u32_e32 v74, -1, v73
	v_add_u32_e32 v75, 1, v73
	v_fma_f32 v76, -v74, v73, v72
	v_fma_f32 v77, -v75, v73, v72
	v_cmp_ge_f32_e64 s[0:1], 0, v76
	s_nop 1
	v_cndmask_b32_e64 v73, v73, v74, s[0:1]
	v_cmp_lt_f32_e64 s[0:1], 0, v77
	s_nop 1
	v_cndmask_b32_e64 v73, v73, v75, s[0:1]
	v_mul_f32_e32 v74, 0x37800000, v73
	v_cndmask_b32_e32 v73, v73, v74, vcc
	v_cmp_class_f32_e32 vcc, v72, v71
	s_nop 1
	v_cndmask_b32_e32 v72, v73, v72, vcc
	v_div_scale_f32 v73, s[0:1], v72, v72, 1.0
	v_rcp_f32_e32 v75, v73
	v_div_scale_f32 v74, vcc, 1.0, v72, 1.0
	v_fma_f32 v76, -v73, v75, 1.0
	v_fmac_f32_e32 v75, v76, v75
	v_mul_f32_e32 v76, v74, v75
	v_fma_f32 v77, -v73, v76, v74
	v_fmac_f32_e32 v76, v77, v75
	v_fma_f32 v73, -v73, v76, v74
	v_div_fmas_f32 v73, v73, v75, v76
	v_div_fixup_f32 v72, v73, v72, 1.0
	v_pk_mul_f32 v[16:17], v[72:73], v[16:17] op_sel_hi:[0,1]
	v_pk_mul_f32 v[18:19], v[72:73], v[18:19] op_sel_hi:[0,1]
	v_pk_mul_f32 v[20:21], v[72:73], v[20:21] op_sel_hi:[0,1]
	v_pk_mul_f32 v[22:23], v[72:73], v[22:23] op_sel_hi:[0,1]
	v_pk_mul_f32 v[24:25], v[72:73], v[24:25] op_sel_hi:[0,1]
	v_pk_mul_f32 v[26:27], v[72:73], v[26:27] op_sel_hi:[0,1]
	v_pk_mul_f32 v[28:29], v[72:73], v[28:29] op_sel_hi:[0,1]
	v_pk_mul_f32 v[30:31], v[72:73], v[30:31] op_sel_hi:[0,1]
	v_pk_fma_f32 v[18:19], v[18:19], v[36:37], v[2:3]
	v_pk_fma_f32 v[16:17], v[16:17], v[38:39], v[0:1]
	v_pk_fma_f32 v[22:23], v[22:23], v[40:41], v[6:7]
	v_pk_fma_f32 v[20:21], v[20:21], v[42:43], v[4:5]
	v_pk_fma_f32 v[26:27], v[26:27], v[44:45], v[10:11]
	v_pk_fma_f32 v[24:25], v[24:25], v[46:47], v[8:9]
	v_pk_fma_f32 v[30:31], v[30:31], v[48:49], v[14:15]
	v_pk_fma_f32 v[28:29], v[28:29], v[50:51], v[12:13]
	v_bfe_u32 v72, v16, 16, 1
	v_bfe_u32 v74, v18, 16, 1
	v_bfe_u32 v73, v17, 16, 1
	v_bfe_u32 v75, v19, 16, 1
	v_bfe_u32 v76, v20, 16, 1
	v_bfe_u32 v78, v22, 16, 1
	v_bfe_u32 v80, v24, 16, 1
	v_bfe_u32 v82, v26, 16, 1
	v_bfe_u32 v84, v28, 16, 1
	v_bfe_u32 v86, v30, 16, 1
	v_add3_u32 v16, v16, v72, s23
	v_add3_u32 v18, v18, v74, s23
	v_bfe_u32 v77, v21, 16, 1
	v_bfe_u32 v79, v23, 16, 1
	v_bfe_u32 v81, v25, 16, 1
	v_bfe_u32 v83, v27, 16, 1
	v_bfe_u32 v85, v29, 16, 1
	v_bfe_u32 v87, v31, 16, 1
	v_add3_u32 v17, v17, v73, s23
	v_add3_u32 v19, v19, v75, s23
	v_add3_u32 v20, v20, v76, s23
	v_add3_u32 v22, v22, v78, s23
	v_add3_u32 v24, v24, v80, s23
	v_add3_u32 v26, v26, v82, s23
	v_add3_u32 v28, v28, v84, s23
	v_add3_u32 v30, v30, v86, s23
	v_lshrrev_b32_e32 v16, 16, v16
	v_lshrrev_b32_e32 v18, 16, v18
	v_add3_u32 v21, v21, v77, s23
	v_add3_u32 v23, v23, v79, s23
	v_add3_u32 v25, v25, v81, s23
	v_add3_u32 v27, v27, v83, s23
	v_add3_u32 v29, v29, v85, s23
	v_add3_u32 v31, v31, v87, s23
	v_lshrrev_b32_e32 v20, 16, v20
	v_lshrrev_b32_e32 v22, 16, v22
	v_lshrrev_b32_e32 v24, 16, v24
	v_lshrrev_b32_e32 v26, 16, v26
	v_lshrrev_b32_e32 v28, 16, v28
	v_lshrrev_b32_e32 v30, 16, v30
	v_and_or_b32 v16, v17, s27, v16
	v_and_or_b32 v17, v19, s27, v18
	v_and_or_b32 v18, v21, s27, v20
	v_and_or_b32 v19, v23, s27, v22
	v_and_or_b32 v20, v25, s27, v24
	v_and_or_b32 v21, v27, s27, v26
	v_and_or_b32 v22, v29, s27, v28
	v_and_or_b32 v23, v31, s27, v30
	global_store_dwordx2 v[52:53], v[16:17], off offset:-1024 sc0 sc1 nt
	global_store_dwordx2 v[52:53], v[18:19], off offset:-512 sc0 sc1 nt
	global_store_dwordx2 v[52:53], v[20:21], off sc0 sc1 nt
	global_store_dwordx2 v[52:53], v[22:23], off offset:512 sc0 sc1 nt
	v_lshl_add_u64 v[52:53], v[52:53], 0, s[56:57]
	s_cbranch_scc0 .LBB0_135
	s_branch .LBB0_112
